# norm1 (phase 1) row loop: scale/shift/gain vector chunks of a row all loaded at the row start instead of serialized load->wait->store per chunk
# speedup vs baseline: 1.0038x; 1.0006x over previous
.LBB0_582:
	s_or_b64 exec, exec, s[16:17]
	v_lshl_add_u64 v[2:3], v[2:3], 0, v[0:1]
	global_load_dwordx4 v[76:79], v[2:3], off
	global_load_dwordx4 v[26:29], v[2:3], off offset:1024
	global_load_dwordx4 v[22:25], v[2:3], off offset:2048
	global_load_dwordx4 v[18:21], v[2:3], off offset:3072
	v_add_co_u32_e32 v2, vcc, s52, v2
	s_movk_i32 s16, 0x3fff
	s_nop 0
	v_addc_co_u32_e32 v3, vcc, 0, v3, vcc
	global_load_dwordx4 v[14:17], v[2:3], off
	global_load_dwordx4 v[10:13], v[2:3], off offset:1024
	global_load_dwordx4 v[6:9], v[2:3], off offset:2048
	s_nop 0
	global_load_dwordx4 v[2:5], v[2:3], off offset:3072
	v_cmp_lt_i32_e32 vcc, s16, v62
	v_mov_b32_e32 v65, v1
	v_mov_b32_e32 v47, v1
	v_cndmask_b32_e32 v33, 0, v64, vcc
	v_lshlrev_b32_e32 v64, 2, v33
	v_lshl_add_u64 v[64:65], s[4:5], 0, v[64:65]
	s_mov_b64 s[16:17], 0x2000
	v_lshl_add_u64 v[66:67], v[64:65], 0, s[16:17]
	v_lshl_add_u64 v[92:93], v[64:65], 0, v[46:47]
	global_load_dwordx4 v[80:83], v[34:35], off
	v_lshl_add_u64 v[68:69], v[66:67], 0, v[46:47]
	global_load_dwordx4 v[84:87], v[92:93], off
	global_load_dwordx4 v[88:91], v[68:69], off
	global_load_dwordx4 v[108:111], v[34:35], off offset:1024
	global_load_dwordx4 v[112:115], v[34:35], off offset:2048
	global_load_dwordx4 v[116:119], v[34:35], off offset:3072
	global_load_dwordx4 v[120:123], v[36:37], off
	global_load_dwordx4 v[124:127], v[38:39], off
	global_load_dwordx4 v[128:131], v[40:41], off
	global_load_dwordx4 v[132:135], v[42:43], off
	v_add_co_u32_e32 v204, vcc, v66, v48
	s_nop 1
	v_addc_co_u32_e32 v205, vcc, 0, v67, vcc
	global_load_dwordx4 v[136:139], v[204:205], off
	global_load_dwordx4 v[168:171], v[92:93], off offset:1024
	v_add_co_u32_e32 v204, vcc, v66, v50
	s_nop 1
	v_addc_co_u32_e32 v205, vcc, 0, v67, vcc
	global_load_dwordx4 v[140:143], v[204:205], off
	global_load_dwordx4 v[172:175], v[92:93], off offset:2048
	v_add_co_u32_e32 v204, vcc, v66, v52
	s_nop 1
	v_addc_co_u32_e32 v205, vcc, 0, v67, vcc
	global_load_dwordx4 v[144:147], v[204:205], off
	global_load_dwordx4 v[176:179], v[92:93], off offset:3072
	v_add_co_u32_e32 v204, vcc, v66, v54
	s_nop 1
	v_addc_co_u32_e32 v205, vcc, 0, v67, vcc
	global_load_dwordx4 v[148:151], v[204:205], off
	v_add_co_u32_e32 v204, vcc, v64, v54
	s_nop 1
	v_addc_co_u32_e32 v205, vcc, 0, v65, vcc
	global_load_dwordx4 v[180:183], v[204:205], off
	v_add_co_u32_e32 v204, vcc, v66, v56
	s_nop 1
	v_addc_co_u32_e32 v205, vcc, 0, v67, vcc
	global_load_dwordx4 v[156:159], v[204:205], off
	v_add_co_u32_e32 v204, vcc, v64, v56
	s_nop 1
	v_addc_co_u32_e32 v205, vcc, 0, v65, vcc
	global_load_dwordx4 v[184:187], v[204:205], off
	v_add_co_u32_e32 v204, vcc, v66, v58
	s_nop 1
	v_addc_co_u32_e32 v205, vcc, 0, v67, vcc
	global_load_dwordx4 v[160:163], v[204:205], off
	v_add_co_u32_e32 v204, vcc, v64, v58
	s_nop 1
	v_addc_co_u32_e32 v205, vcc, 0, v65, vcc
	global_load_dwordx4 v[188:191], v[204:205], off
	v_add_co_u32_e32 v204, vcc, v66, v60
	s_nop 1
	v_addc_co_u32_e32 v205, vcc, 0, v67, vcc
	global_load_dwordx4 v[164:167], v[204:205], off
	v_add_co_u32_e32 v204, vcc, v64, v60
	s_nop 1
	v_addc_co_u32_e32 v205, vcc, 0, v65, vcc
	global_load_dwordx4 v[192:195], v[204:205], off
	s_waitcnt vmcnt(0)
	v_mul_f32_e32 v33, v77, v77
	v_mul_f32_e32 v47, v27, v27
	v_mul_f32_e32 v49, v23, v23
	v_fmac_f32_e32 v33, v76, v76
	v_fmac_f32_e32 v47, v26, v26
	v_mul_f32_e32 v51, v19, v19
	v_fmac_f32_e32 v49, v22, v22
	v_mov_b32_e32 v94, v15
	v_mov_b32_e32 v95, v11
	v_fmac_f32_e32 v33, v78, v78
	v_fmac_f32_e32 v47, v28, v28
	v_fmac_f32_e32 v51, v18, v18
	v_mov_b32_e32 v68, v14
	v_mov_b32_e32 v69, v10
	v_fmac_f32_e32 v49, v24, v24
	v_pk_mul_f32 v[94:95], v[94:95], v[94:95]
	v_fmac_f32_e32 v33, v79, v79
	v_fmac_f32_e32 v47, v29, v29
	v_mov_b32_e32 v96, v16
	v_mov_b32_e32 v97, v12
	v_mov_b32_e32 v102, v7
	v_mov_b32_e32 v103, v3
	v_fmac_f32_e32 v51, v20, v20
	v_fmac_f32_e32 v49, v25, v25
	v_pk_fma_f32 v[68:69], v[68:69], v[68:69], v[94:95]
	v_add_f32_e32 v33, v33, v47
	v_mov_b32_e32 v98, v17
	v_mov_b32_e32 v99, v13
	v_mov_b32_e32 v100, v6
	v_mov_b32_e32 v101, v2
	v_pk_mul_f32 v[102:103], v[102:103], v[102:103]
	v_fmac_f32_e32 v51, v21, v21
	v_pk_fma_f32 v[68:69], v[96:97], v[96:97], v[68:69]
	v_add_f32_e32 v33, v33, v49
	v_mov_b32_e32 v104, v8
	v_mov_b32_e32 v105, v4
	v_pk_fma_f32 v[94:95], v[100:101], v[100:101], v[102:103]
	v_pk_fma_f32 v[68:69], v[98:99], v[98:99], v[68:69]
	v_add_f32_e32 v33, v33, v51
	v_mov_b32_e32 v106, v9
	v_mov_b32_e32 v107, v5
	v_pk_fma_f32 v[94:95], v[104:105], v[104:105], v[94:95]
	v_add_f32_e32 v33, v33, v68
	v_pk_fma_f32 v[94:95], v[106:107], v[106:107], v[94:95]
	v_add_f32_e32 v33, v33, v69
	v_add_f32_e32 v33, v33, v94
	v_add_f32_e32 v33, v33, v95
	ds_bpermute_b32 v47, v70, v33
	v_lshlrev_b64 v[68:69], 12, v[62:63]
	v_mov_b32_e32 v49, v1
	v_lshl_add_u64 v[68:69], v[44:45], 0, v[68:69]
	v_lshl_add_u64 v[94:95], v[66:67], 0, v[48:49]
	s_waitcnt lgkmcnt(0)
	v_add_f32_e32 v33, v33, v47
	ds_bpermute_b32 v47, v71, v33
	v_add_f32_e32 v49, 1.0, v88
	v_add_f32_e32 v51, 1.0, v90
	v_add_f32_e32 v53, 1.0, v91
	s_waitcnt lgkmcnt(0)
	v_add_f32_e32 v33, v33, v47
	ds_bpermute_b32 v47, v72, v33
	s_waitcnt lgkmcnt(0)
	v_add_f32_e32 v33, v33, v47
	ds_bpermute_b32 v47, v73, v33
	s_waitcnt lgkmcnt(0)
	v_add_f32_e32 v33, v33, v47
	ds_bpermute_b32 v47, v74, v33
	s_waitcnt lgkmcnt(0)
	v_add_f32_e32 v33, v33, v47
	ds_bpermute_b32 v47, v75, v33
	s_waitcnt lgkmcnt(0)
	v_add_f32_e32 v33, v33, v47
	v_fmamk_f32 v33, v33, 0x3a000000, v207
	v_mul_f32_e32 v47, 0x4b800000, v33
	v_cmp_gt_f32_e32 vcc, s33, v33
	s_nop 1
	v_cndmask_b32_e32 v33, v33, v47, vcc
	v_rsq_f32_e32 v33, v33
	v_add_f32_e32 v47, 1.0, v89
	v_mul_f32_e32 v55, 0x45800000, v33
	v_cndmask_b32_e32 v33, v33, v55, vcc
	v_mul_f32_e32 v55, v76, v33
	v_mul_f32_e32 v57, v77, v33
	v_mul_f32_e32 v59, v78, v33
	v_mul_f32_e32 v61, v79, v33
	v_mul_f32_e32 v55, v80, v55
	v_mul_f32_e32 v57, v81, v57
	v_mul_f32_e32 v59, v82, v59
	v_mul_f32_e32 v61, v83, v61
	v_fma_f32 v49, v49, v55, v84
	v_fma_f32 v47, v47, v57, v85
	v_fma_f32 v51, v51, v59, v86
	v_fmac_f32_e32 v87, v53, v61
	v_cvt_pk_bf16_f32 v76, v49, v47
	v_cvt_pk_bf16_f32 v77, v51, v87
	global_store_dwordx2 v[68:69], v[76:77], off
	s_nop 0
	v_mul_f32_e32 v26, v26, v33
	v_mul_f32_e32 v27, v27, v33
	v_mov_b32_e32 v51, v1
	v_mul_f32_e32 v28, v28, v33
	v_mul_f32_e32 v29, v29, v33
	v_lshl_add_u64 v[88:89], v[66:67], 0, v[50:51]
	v_mul_f32_e32 v22, v22, v33
	v_mul_f32_e32 v23, v23, v33
	v_mul_f32_e32 v24, v24, v33
	v_mul_f32_e32 v25, v25, v33
	v_mul_f32_e32 v18, v18, v33
	v_mul_f32_e32 v19, v19, v33
	v_mul_f32_e32 v20, v20, v33
	v_mul_f32_e32 v21, v21, v33
	v_mov_b32_e32 v55, v1
	v_mul_f32_e32 v14, v14, v33
	v_mul_f32_e32 v15, v15, v33
	v_mul_f32_e32 v16, v16, v33
	v_mul_f32_e32 v17, v17, v33
	v_mov_b32_e32 v57, v1
	v_mul_f32_e32 v10, v10, v33
	v_mul_f32_e32 v11, v11, v33
	v_mul_f32_e32 v12, v12, v33
	v_mul_f32_e32 v13, v13, v33
	v_mov_b32_e32 v59, v1
	v_mul_f32_e32 v6, v6, v33
	v_mul_f32_e32 v7, v7, v33
	v_mul_f32_e32 v8, v8, v33
	v_mul_f32_e32 v9, v9, v33
	v_mov_b32_e32 v61, v1
	v_mul_f32_e32 v2, v2, v33
	v_mul_f32_e32 v3, v3, v33
	v_mul_f32_e32 v4, v4, v33
	v_mul_f32_e32 v5, v5, v33
	v_mul_f32_e32 v26, v108, v26
	v_add_f32_e32 v47, 1.0, v136
	v_mul_f32_e32 v27, v109, v27
	v_add_f32_e32 v49, 1.0, v137
	v_mul_f32_e32 v28, v110, v28
	v_add_f32_e32 v51, 1.0, v138
	v_mul_f32_e32 v29, v111, v29
	v_add_f32_e32 v53, 1.0, v139
	v_fma_f32 v26, v47, v26, v168
	v_fma_f32 v27, v49, v27, v169
	v_fma_f32 v28, v51, v28, v170
	v_fmac_f32_e32 v171, v53, v29
	v_cvt_pk_bf16_f32 v26, v26, v27
	v_cvt_pk_bf16_f32 v27, v28, v171
	global_store_dwordx2 v[68:69], v[26:27], off offset:512
	s_nop 0
	v_mov_b32_e32 v53, v1
	v_lshl_add_u64 v[84:85], v[66:67], 0, v[52:53]
	v_mul_f32_e32 v22, v22, v112
	v_add_f32_e32 v112, 1.0, v140
	v_mul_f32_e32 v23, v23, v113
	v_add_f32_e32 v113, 1.0, v141
	v_mul_f32_e32 v24, v24, v114
	v_add_f32_e32 v114, 1.0, v142
	v_mul_f32_e32 v25, v25, v115
	v_add_f32_e32 v115, 1.0, v143
	v_fma_f32 v22, v22, v112, v172
	v_fma_f32 v23, v23, v113, v173
	v_fma_f32 v24, v24, v114, v174
	v_fmac_f32_e32 v175, v25, v115
	v_cvt_pk_bf16_f32 v22, v22, v23
	v_cvt_pk_bf16_f32 v23, v24, v175
	global_store_dwordx2 v[68:69], v[22:23], off offset:1024
	s_nop 0
	v_lshl_add_u64 v[80:81], v[66:67], 0, v[54:55]
	v_mul_f32_e32 v18, v18, v116
	v_add_f32_e32 v116, 1.0, v144
	v_mul_f32_e32 v19, v19, v117
	v_add_f32_e32 v117, 1.0, v145
	v_mul_f32_e32 v20, v20, v118
	v_add_f32_e32 v118, 1.0, v146
	v_mul_f32_e32 v21, v21, v119
	v_add_f32_e32 v119, 1.0, v147
	v_fma_f32 v18, v18, v116, v176
	v_fma_f32 v19, v19, v117, v177
	v_fma_f32 v20, v20, v118, v178
	v_fmac_f32_e32 v179, v21, v119
	v_cvt_pk_bf16_f32 v18, v18, v19
	v_cvt_pk_bf16_f32 v19, v20, v179
	global_store_dwordx2 v[68:69], v[18:19], off offset:1536
	s_nop 0
	v_lshl_add_u64 v[76:77], v[66:67], 0, v[56:57]
	v_mul_f32_e32 v14, v14, v120
	v_add_f32_e32 v120, 1.0, v148
	v_mul_f32_e32 v15, v15, v121
	v_add_f32_e32 v121, 1.0, v149
	v_mul_f32_e32 v16, v16, v122
	v_add_f32_e32 v122, 1.0, v150
	v_mul_f32_e32 v17, v17, v123
	v_add_f32_e32 v123, 1.0, v151
	v_fma_f32 v14, v14, v120, v180
	v_fma_f32 v15, v15, v121, v181
	v_fma_f32 v16, v16, v122, v182
	v_fmac_f32_e32 v183, v17, v123
	v_cvt_pk_bf16_f32 v14, v14, v15
	v_cvt_pk_bf16_f32 v15, v16, v183
	global_store_dwordx2 v[68:69], v[14:15], off offset:2048
	s_nop 0
	v_lshl_add_u64 v[26:27], v[66:67], 0, v[58:59]
	v_mul_f32_e32 v10, v10, v124
	v_add_f32_e32 v124, 1.0, v156
	v_mul_f32_e32 v11, v11, v125
	v_add_f32_e32 v125, 1.0, v157
	v_mul_f32_e32 v12, v12, v126
	v_add_f32_e32 v126, 1.0, v158
	v_mul_f32_e32 v13, v13, v127
	v_add_f32_e32 v127, 1.0, v159
	v_fma_f32 v10, v10, v124, v184
	v_fma_f32 v11, v11, v125, v185
	v_fma_f32 v12, v12, v126, v186
	v_fmac_f32_e32 v187, v13, v127
	v_cvt_pk_bf16_f32 v10, v10, v11
	v_cvt_pk_bf16_f32 v11, v12, v187
	global_store_dwordx2 v[68:69], v[10:11], off offset:2560
	s_nop 0
	v_lshl_add_u64 v[22:23], v[66:67], 0, v[60:61]
	v_mul_f32_e32 v6, v6, v128
	v_add_f32_e32 v128, 1.0, v160
	v_mul_f32_e32 v7, v7, v129
	v_add_f32_e32 v129, 1.0, v161
	v_mul_f32_e32 v8, v8, v130
	v_add_f32_e32 v130, 1.0, v162
	v_mul_f32_e32 v9, v9, v131
	v_add_f32_e32 v131, 1.0, v163
	v_fma_f32 v6, v6, v128, v188
	v_fma_f32 v7, v7, v129, v189
	v_fma_f32 v8, v8, v130, v190
	v_fmac_f32_e32 v191, v9, v131
	v_cvt_pk_bf16_f32 v6, v6, v7
	v_cvt_pk_bf16_f32 v7, v8, v191
	global_store_dwordx2 v[68:69], v[6:7], off offset:3072
	s_nop 0
	v_mul_f32_e32 v2, v2, v132
	v_add_f32_e32 v132, 1.0, v164
	v_mul_f32_e32 v3, v3, v133
	v_add_f32_e32 v133, 1.0, v165
	v_mul_f32_e32 v4, v4, v134
	v_add_f32_e32 v134, 1.0, v166
	v_mul_f32_e32 v5, v5, v135
	v_add_f32_e32 v135, 1.0, v167
	v_fma_f32 v2, v2, v132, v192
	v_fma_f32 v3, v3, v133, v193
	v_fma_f32 v4, v4, v134, v194
	v_fmac_f32_e32 v195, v5, v135
	v_cvt_pk_bf16_f32 v2, v2, v3
	v_cvt_pk_bf16_f32 v3, v4, v195
	global_store_dwordx2 v[68:69], v[2:3], off offset:3584
	s_load_dword s16, s[98:99], 0x10
	s_waitcnt lgkmcnt(0)
	s_lshr_b32 s16, s16, 16
	s_cmp_lg_u32 s16, 0
	s_cselect_b64 s[16:17], -1, 0
	s_cmp_lg_u64 s[16:17], 0
	s_addc_u32 s16, s28, 0
	v_lshl_add_u32 v62, s16, 3, v62
	s_mov_b32 s16, 0x81ff
	v_cmp_lt_i32_e32 vcc, s16, v62
	s_or_b64 s[6:7], vcc, s[6:7]
	s_andn2_b64 exec, exec, s[6:7]
	s_cbranch_execz .LBB0_587
